# v82 + A/B GLU assignment: even panels compute all GLU tiles, odd panels run ahead
# baseline (speedup 1.0000x reference)
.LBB0_589:
	s_cmp_gt_i32 s26, 4
	s_cselect_b64 s[4:5], -1, 0
	s_xor_b64 s[0:1], s[0:1], -1
	s_or_b64 s[0:1], s[4:5], s[0:1]
	s_and_b64 vcc, exec, s[0:1]
	s_cbranch_vccnz .LBB0_771
	v_and_b32_e32 v231, 0x3ff, v0
	v_lshlrev_b32_e32 v1, 4, v231
	v_and_b32_e32 v2, 32, v0
	v_bitop3_b32 v229, v1, v2, 48 bitop3:0x6c
	v_lshrrev_b32_e32 v2, 5, v0
	v_lshrrev_b32_e32 v4, 1, v0
	v_and_b32_e32 v2, 4, v2
	v_bfe_u32 v3, v231, 2, 2
	v_and_b32_e32 v236, 24, v4
	v_bfe_u32 v232, v231, 2, 4
	v_and_b32_e32 v230, 64, v0
	v_or3_b32 v2, v2, v3, v236
	v_bfe_u32 v0, v0, 3, 7
	v_or_b32_e32 v233, 0x2000, v1
	v_and_or_b32 v240, v0, 48, v232
	v_and_or_b32 v241, v0, 32, v2
	v_lshrrev_b32_e32 v0, 7, v233
	s_movk_i32 s1, 0x70
	v_and_or_b32 v243, v0, s1, v232
	s_movk_i32 s1, 0x60
	v_and_or_b32 v242, v0, s1, v2
	v_lshlrev_b32_e32 v0, 6, v231
	s_add_u32 s4, s76, 0x1000000
	v_and_b32_e32 v234, 0x3c0, v0
	v_lshlrev_b32_e32 v0, 2, v231
	s_addc_u32 s40, s77, 0
	v_or_b32_e32 v239, v229, v230
	v_lshlrev_b32_e32 v237, 1, v236
	v_and_b32_e32 v235, 32, v0
	v_readfirstlane_b32 s0, v231
	v_lshl_or_b32 v208, v240, 10, v239
	v_lshl_or_b32 v210, v241, 10, v239
	v_lshl_or_b32 v212, v243, 10, v239
	v_lshl_or_b32 v214, v242, 10, v239
	s_bitcmp1_b32 s96, 3
	v_bitop3_b32 v238, v237, v235, v234 bitop3:0x36
	s_cbranch_scc1 .LBB0_610
	s_lshl_b32 s2, s96, 3
	s_and_b32 s2, s2, 56
	s_bfe_u32 s6, s96, 0x30003
	s_lshr_b32 s5, s0, 6
	s_or_b32 s2, s2, s6
	s_bfe_u32 s6, s96, 0x50006
	s_lshr_b32 s98, s96, 7
	s_add_i32 s2, s2, s98
	s_and_b32 s6, s6, 1
	s_lshr_b32 s1, s0, 8
	s_lshl_b32 s33, s5, 10
	s_lshl_b32 s7, s2, 18
	s_lshl_b32 s8, s6, 18
	s_add_u32 s36, s78, s8
	s_addc_u32 s37, s79, 0
	s_add_i32 s41, s33, 0
	s_add_i32 m0, s41, 0x10000
	v_mov_b32_e32 v211, 0
	global_load_lds_dwordx4 v210, s[36:37]
	s_add_i32 m0, s41, 0x12000
	s_add_u32 s8, s36, 0x20000
	global_load_lds_dwordx4 v214, s[36:37]
	s_addc_u32 s9, s37, 0
	s_add_i32 m0, s41, 0x14000
	v_mov_b32_e32 v215, v211
	global_load_lds_dwordx4 v210, s[8:9]
	s_add_i32 m0, s41, 0x16000
	s_add_u32 s34, s76, s7
	s_addc_u32 s35, s77, 0
	s_add_i32 s42, s41, 0x2000
	global_load_lds_dwordx4 v214, s[8:9]
	s_mov_b32 m0, s41
	s_add_u32 s8, s34, 0x20000
	global_load_lds_dwordx4 v208, s[34:35]
	s_mov_b32 m0, s42
	s_addc_u32 s9, s35, 0
	s_add_i32 s43, s41, 0x4000
	global_load_lds_dwordx4 v212, s[34:35]
	s_mov_b32 m0, s43
	s_add_i32 s44, s41, 0x6000
	global_load_lds_dwordx4 v208, s[8:9]
	s_mov_b32 m0, s44
	v_mov_b32_e32 v209, v211
	global_load_lds_dwordx4 v212, s[8:9]
	v_mov_b32_e32 v213, v211
	s_cmp_eq_u32 s1, 1
	s_mov_b32 s45, 0
	v_lshl_add_u64 v[6:7], s[36:37], 0, v[210:211]
	v_lshl_add_u64 v[2:3], s[36:37], 0, v[214:215]
	s_mov_b64 s[8:9], 0x20000
	v_lshl_add_u64 v[0:1], s[34:35], 0, v[208:209]
	s_cselect_b64 s[10:11], -1, 0
	s_cmp_lg_u32 s1, 1
	v_lshl_add_u64 v[4:5], s[34:35], 0, v[212:213]
	s_cbranch_scc1 .LBB0_593
	s_barrier

.LBB0_610:
	s_cmpk_eq_i32 s3, 0x100
	s_cselect_b64 s[6:7], -1, 0
	s_bitcmp0_b32 s96, 3
	v_cmp_eq_u32_e64 s[0:1], 0, v231
	s_cselect_b64 s[2:3], -1, 0
	s_and_b64 s[8:9], s[0:1], s[6:7]
	s_and_b64 s[2:3], s[8:9], s[2:3]
	s_and_saveexec_b64 s[8:9], s[2:3]
	s_cbranch_execz .LBB0_613
	s_mov_b64 s[10:11], exec
	v_mbcnt_lo_u32_b32 v0, s10, 0
	v_mbcnt_hi_u32_b32 v0, s11, v0
	v_cmp_eq_u32_e32 vcc, 0, v0
	s_and_b64 s[2:3], exec, vcc
	s_mov_b64 exec, s[2:3]
	s_cbranch_execz .LBB0_613
	s_lshl_b32 s2, s96, 3
	s_and_b32 s2, s2, 56
	s_bfe_u32 s3, s96, 0x30003
	s_or_b32 s2, s2, s3
	s_lshr_b32 s3, s96, 7
	s_add_i32 s2, s2, s3
	s_lshl_b32 s2, s2, 8
	s_add_u32 s2, s78, s2
	s_addc_u32 s3, s79, 0
	s_bcnt1_i32_b64 s5, s[10:11]
	v_mov_b32_e32 v0, 0xe81e000
	v_mov_b32_e32 v1, s5
	global_atomic_add v0, v1, s[2:3]
